# v058 with a 2us/XCD start stagger (XCD_SLEEP=64)
# speedup vs baseline: 1.0025x; 1.0025x over previous
.Lxl_stag_loop:
	s_sleep 64
	s_add_i32 s101, s101, -1
	s_cmp_lg_u32 s101, 0
	s_cbranch_scc1 .Lxl_stag_loop
